# attention steady loops: exact skip of a tile's exp/sum/PV when every probability of the block underflows to +0 (block max <= running max - 152 in log2 units)
# speedup vs baseline: 1.0097x; 1.0097x over previous
.Ldf_itera:
	v_mfma_f32_32x32x16_bf16 v[2:17], v[170:173], v[130:133], v[114:129]
	v_mfma_f32_32x32x16_bf16 v[18:33], v[170:173], v[138:141], v[114:129]
	v_mfma_f32_32x32x16_bf16 v[2:17], v[174:177], v[134:137], v[2:17]
	v_mfma_f32_32x32x16_bf16 v[18:33], v[174:177], v[142:145], v[18:33]
	v_mul_f32_e64 v198, -v200, v205
	v_fmamk_f32 v199, v200, 0xc2000000, v198
	v_add_f32_e32 v205, 0x42000000, v205
	s_nop 7
	v_max3_f32 v206, v2, v3, v4
	v_max3_f32 v207, v5, v6, v7
	v_max3_f32 v208, v8, v9, v10
	v_max3_f32 v209, v11, v12, v13
	v_max3_f32 v206, v206, v14, v15
	v_max3_f32 v207, v207, v16, v17
	v_max3_f32 v206, v206, v207, v208
	v_max_f32_e32 v206, v206, v209
	v_fma_f32 v206, v206, s98, v198
	v_mov_b32_e32 v207, v206
	s_nop 1
	v_permlane32_swap_b32_e32 v206, v207
	v_max3_f32 v194, v188, v206, v207
	v_sub_f32_e32 v208, v188, v194
	v_sub_f32_e32 v196, v198, v194
	v_exp_f32_e32 v190, v208
	v_max_f32_e32 v209, v206, v207
	v_sub_f32_e32 v209, v209, v188
	v_cmp_lt_f32_e32 vcc, 0xc3180000, v209
	s_cbranch_vccz .Ldf_sk0a
	v_fma_f32 v2, v2, s98, v196
	v_fma_f32 v3, v3, s98, v196
	v_fma_f32 v4, v4, s98, v196
	v_fma_f32 v5, v5, s98, v196
	v_fma_f32 v6, v6, s98, v196
	v_fma_f32 v7, v7, s98, v196
	v_fma_f32 v8, v8, s98, v196
	v_fma_f32 v9, v9, s98, v196
	v_fma_f32 v10, v10, s98, v196
	v_fma_f32 v11, v11, s98, v196
	v_fma_f32 v12, v12, s98, v196
	v_fma_f32 v13, v13, s98, v196
	v_fma_f32 v14, v14, s98, v196
	v_fma_f32 v15, v15, s98, v196
	v_fma_f32 v16, v16, s98, v196
	v_fma_f32 v17, v17, s98, v196
	v_exp_f32_e32 v2, v2
	v_exp_f32_e32 v3, v3
	v_exp_f32_e32 v4, v4
	v_exp_f32_e32 v5, v5
	v_exp_f32_e32 v6, v6
	v_exp_f32_e32 v7, v7
	v_exp_f32_e32 v8, v8
	v_exp_f32_e32 v9, v9
	v_exp_f32_e32 v10, v10
	v_exp_f32_e32 v11, v11
	v_exp_f32_e32 v12, v12
	v_exp_f32_e32 v13, v13
	v_exp_f32_e32 v14, v14
	v_exp_f32_e32 v15, v15
	v_exp_f32_e32 v16, v16
	v_exp_f32_e32 v17, v17
	v_cmp_lt_f32_e32 vcc, v188, v194
	v_mov_b32_e32 v188, v194
	v_cvt_pk_bf16_f32 v98, v2, v3
	v_cvt_pk_bf16_f32 v99, v4, v5
	v_cvt_pk_bf16_f32 v100, v6, v7
	v_cvt_pk_bf16_f32 v101, v8, v9
	v_cvt_pk_bf16_f32 v102, v10, v11
	v_cvt_pk_bf16_f32 v103, v12, v13
	v_cvt_pk_bf16_f32 v104, v14, v15
	v_cvt_pk_bf16_f32 v105, v16, v17
	v_add_f32_e32 v206, v2, v3
	v_add_f32_e32 v207, v4, v5
	v_add_f32_e32 v208, v6, v7
	v_add_f32_e32 v209, v8, v9
	v_add_f32_e32 v206, v206, v10
	v_add_f32_e32 v207, v207, v11
	v_add_f32_e32 v208, v208, v12
	v_add_f32_e32 v209, v209, v13
	v_add_f32_e32 v206, v206, v14
	v_add_f32_e32 v207, v207, v15
	v_add_f32_e32 v208, v208, v16
	v_add_f32_e32 v209, v209, v17
	v_add_f32_e32 v206, v206, v207
	v_add_f32_e32 v208, v208, v209
	v_add_f32_e32 v206, v206, v208
	v_fmac_f32_e32 v206, v182, v190
	v_mov_b32_e32 v182, v206
	s_cbranch_vccz .Ldf_nr0a
	v_pk_mul_f32 v[82:83], v[82:83], v[190:191] op_sel_hi:[1,0]
	v_pk_mul_f32 v[84:85], v[84:85], v[190:191] op_sel_hi:[1,0]
	v_pk_mul_f32 v[86:87], v[86:87], v[190:191] op_sel_hi:[1,0]
	v_pk_mul_f32 v[88:89], v[88:89], v[190:191] op_sel_hi:[1,0]
	v_pk_mul_f32 v[90:91], v[90:91], v[190:191] op_sel_hi:[1,0]
	v_pk_mul_f32 v[92:93], v[92:93], v[190:191] op_sel_hi:[1,0]
	v_pk_mul_f32 v[94:95], v[94:95], v[190:191] op_sel_hi:[1,0]
	v_pk_mul_f32 v[96:97], v[96:97], v[190:191] op_sel_hi:[1,0]
	v_pk_mul_f32 v[66:67], v[66:67], v[190:191] op_sel_hi:[1,0]
	v_pk_mul_f32 v[68:69], v[68:69], v[190:191] op_sel_hi:[1,0]
	v_pk_mul_f32 v[70:71], v[70:71], v[190:191] op_sel_hi:[1,0]
	v_pk_mul_f32 v[72:73], v[72:73], v[190:191] op_sel_hi:[1,0]
	v_pk_mul_f32 v[74:75], v[74:75], v[190:191] op_sel_hi:[1,0]
	v_pk_mul_f32 v[76:77], v[76:77], v[190:191] op_sel_hi:[1,0]
	v_pk_mul_f32 v[78:79], v[78:79], v[190:191] op_sel_hi:[1,0]
	v_pk_mul_f32 v[80:81], v[80:81], v[190:191] op_sel_hi:[1,0]
	s_nop 1

.Ldf_sk0a:
	v_max3_f32 v210, v18, v19, v20
	v_max3_f32 v211, v21, v22, v23
	v_max3_f32 v215, v24, v25, v26
	v_max3_f32 v216, v27, v28, v29
	v_max3_f32 v210, v210, v30, v31
	v_max3_f32 v211, v211, v32, v33
	v_max3_f32 v210, v210, v211, v215
	v_max_f32_e32 v210, v210, v216
	v_fma_f32 v210, v210, s98, v199
	v_mov_b32_e32 v211, v210
	s_nop 1
	v_permlane32_swap_b32_e32 v210, v211
	v_max3_f32 v195, v0, v210, v211
	v_sub_f32_e32 v215, v0, v195
	v_sub_f32_e32 v197, v199, v195
	v_exp_f32_e32 v192, v215
	v_max_f32_e32 v216, v210, v211
	v_sub_f32_e32 v216, v216, v0
	v_cmp_lt_f32_e32 vcc, 0xc3180000, v216
	s_cbranch_vccz .Ldf_sk1a
	v_fma_f32 v18, v18, s98, v197
	v_fma_f32 v19, v19, s98, v197
	v_fma_f32 v20, v20, s98, v197
	v_fma_f32 v21, v21, s98, v197
	v_fma_f32 v22, v22, s98, v197
	v_fma_f32 v23, v23, s98, v197
	v_fma_f32 v24, v24, s98, v197
	v_fma_f32 v25, v25, s98, v197
	v_fma_f32 v26, v26, s98, v197
	v_fma_f32 v27, v27, s98, v197
	v_fma_f32 v28, v28, s98, v197
	v_fma_f32 v29, v29, s98, v197
	v_fma_f32 v30, v30, s98, v197
	v_fma_f32 v31, v31, s98, v197
	v_fma_f32 v32, v32, s98, v197
	v_fma_f32 v33, v33, s98, v197
	v_exp_f32_e32 v18, v18
	v_exp_f32_e32 v19, v19
	v_exp_f32_e32 v20, v20
	v_exp_f32_e32 v21, v21
	v_exp_f32_e32 v22, v22
	v_exp_f32_e32 v23, v23
	v_exp_f32_e32 v24, v24
	v_exp_f32_e32 v25, v25
	v_exp_f32_e32 v26, v26
	v_exp_f32_e32 v27, v27
	v_exp_f32_e32 v28, v28
	v_exp_f32_e32 v29, v29
	v_exp_f32_e32 v30, v30
	v_exp_f32_e32 v31, v31
	v_exp_f32_e32 v32, v32
	v_exp_f32_e32 v33, v33
	v_cmp_lt_f32_e32 vcc, v0, v195
	v_mov_b32_e32 v0, v195
	v_cvt_pk_bf16_f32 v106, v18, v19
	v_cvt_pk_bf16_f32 v107, v20, v21
	v_cvt_pk_bf16_f32 v108, v22, v23
	v_cvt_pk_bf16_f32 v109, v24, v25
	v_cvt_pk_bf16_f32 v110, v26, v27
	v_cvt_pk_bf16_f32 v111, v28, v29
	v_cvt_pk_bf16_f32 v112, v30, v31
	v_cvt_pk_bf16_f32 v113, v32, v33
	v_add_f32_e32 v210, v18, v19
	v_add_f32_e32 v211, v20, v21
	v_add_f32_e32 v215, v22, v23
	v_add_f32_e32 v216, v24, v25
	v_add_f32_e32 v210, v210, v26
	v_add_f32_e32 v211, v211, v27
	v_add_f32_e32 v215, v215, v28
	v_add_f32_e32 v216, v216, v29
	v_add_f32_e32 v210, v210, v30
	v_add_f32_e32 v211, v211, v31
	v_add_f32_e32 v215, v215, v32
	v_add_f32_e32 v216, v216, v33
	v_add_f32_e32 v210, v210, v211
	v_add_f32_e32 v215, v215, v216
	v_add_f32_e32 v210, v210, v215
	v_fmac_f32_e32 v210, v183, v192
	v_mov_b32_e32 v183, v210
	s_cbranch_vccz .Ldf_nr1a
	v_pk_mul_f32 v[50:51], v[50:51], v[192:193] op_sel_hi:[1,0]
	v_pk_mul_f32 v[52:53], v[52:53], v[192:193] op_sel_hi:[1,0]
	v_pk_mul_f32 v[54:55], v[54:55], v[192:193] op_sel_hi:[1,0]
	v_pk_mul_f32 v[56:57], v[56:57], v[192:193] op_sel_hi:[1,0]
	v_pk_mul_f32 v[58:59], v[58:59], v[192:193] op_sel_hi:[1,0]
	v_pk_mul_f32 v[60:61], v[60:61], v[192:193] op_sel_hi:[1,0]
	v_pk_mul_f32 v[62:63], v[62:63], v[192:193] op_sel_hi:[1,0]
	v_pk_mul_f32 v[64:65], v[64:65], v[192:193] op_sel_hi:[1,0]
	v_pk_mul_f32 v[34:35], v[34:35], v[192:193] op_sel_hi:[1,0]
	v_pk_mul_f32 v[36:37], v[36:37], v[192:193] op_sel_hi:[1,0]
	v_pk_mul_f32 v[38:39], v[38:39], v[192:193] op_sel_hi:[1,0]
	v_pk_mul_f32 v[40:41], v[40:41], v[192:193] op_sel_hi:[1,0]
	v_pk_mul_f32 v[42:43], v[42:43], v[192:193] op_sel_hi:[1,0]
	v_pk_mul_f32 v[44:45], v[44:45], v[192:193] op_sel_hi:[1,0]
	v_pk_mul_f32 v[46:47], v[46:47], v[192:193] op_sel_hi:[1,0]
	v_pk_mul_f32 v[48:49], v[48:49], v[192:193] op_sel_hi:[1,0]
	s_nop 1
.Ldf_nr1a:
	s_waitcnt vmcnt(2)
	v_mfma_f32_32x32x16_bf16 v[50:65], v[166:169], v[106:109], v[50:65]
	v_mfma_f32_32x32x16_bf16 v[34:49], v[158:161], v[106:109], v[34:49]
	v_mfma_f32_32x32x16_bf16 v[50:65], v[162:165], v[110:113], v[50:65]
	v_mfma_f32_32x32x16_bf16 v[34:49], v[154:157], v[110:113], v[34:49]
.Ldf_sk1a:
	s_and_b64 vcc, exec, s[4:5]
	s_cbranch_vccnz .Ldf_exit
	s_add_i32 s15, s15, -1
	v_lshl_add_u64 v[180:181], v[180:181], 0, s[84:85]
	s_cmp_le_i32 s15, s73
	s_cselect_b64 s[4:5], -1, 0
	s_add_i32 s100, s15, -1
	s_cmp_le_i32 s15, s73
	s_cselect_b32 s76, s15, s100
	s_lshl_b64 s[16:17], s[76:77], 12
	s_waitcnt vmcnt(0)
	global_load_dwordx4 v[166:169], v[180:181], off offset:-2048
	global_load_dwordx4 v[162:165], v[180:181], off offset:-1024
	global_load_dwordx4 v[158:161], v[180:181], off
	global_load_dwordx4 v[154:157], v[180:181], off offset:1024
	v_lshl_add_u64 v[220:221], v[178:179], 0, s[16:17]
	global_load_dwordx4 v[170:173], v[220:221], off
	global_load_dwordx4 v[174:177], v[220:221], off offset:1024
	s_branch .Ldf_iterb
.Ldf_iterb:
	v_mfma_f32_32x32x16_bf16 v[2:17], v[146:149], v[130:133], v[114:129]
	v_mfma_f32_32x32x16_bf16 v[18:33], v[146:149], v[138:141], v[114:129]
	v_mfma_f32_32x32x16_bf16 v[2:17], v[150:153], v[134:137], v[2:17]
	v_mfma_f32_32x32x16_bf16 v[18:33], v[150:153], v[142:145], v[18:33]
	v_mul_f32_e64 v198, -v200, v205
	v_fmamk_f32 v199, v200, 0xc2000000, v198
	v_add_f32_e32 v205, 0x42000000, v205
	s_nop 7
	v_max3_f32 v206, v2, v3, v4
	v_max3_f32 v207, v5, v6, v7
	v_max3_f32 v208, v8, v9, v10
	v_max3_f32 v209, v11, v12, v13
	v_max3_f32 v206, v206, v14, v15
	v_max3_f32 v207, v207, v16, v17
	v_max3_f32 v206, v206, v207, v208
	v_max_f32_e32 v206, v206, v209
	v_fma_f32 v206, v206, s98, v198
	v_mov_b32_e32 v207, v206
	s_nop 1
	v_permlane32_swap_b32_e32 v206, v207
	v_max3_f32 v194, v188, v206, v207
	v_sub_f32_e32 v208, v188, v194
	v_sub_f32_e32 v196, v198, v194
	v_exp_f32_e32 v190, v208
	v_max_f32_e32 v209, v206, v207
	v_sub_f32_e32 v209, v209, v188
	v_cmp_lt_f32_e32 vcc, 0xc3180000, v209
	s_cbranch_vccz .Ldf_sk0b
	v_fma_f32 v2, v2, s98, v196
	v_fma_f32 v3, v3, s98, v196
	v_fma_f32 v4, v4, s98, v196
	v_fma_f32 v5, v5, s98, v196
	v_fma_f32 v6, v6, s98, v196
	v_fma_f32 v7, v7, s98, v196
	v_fma_f32 v8, v8, s98, v196
	v_fma_f32 v9, v9, s98, v196
	v_fma_f32 v10, v10, s98, v196
	v_fma_f32 v11, v11, s98, v196
	v_fma_f32 v12, v12, s98, v196
	v_fma_f32 v13, v13, s98, v196
	v_fma_f32 v14, v14, s98, v196
	v_fma_f32 v15, v15, s98, v196
	v_fma_f32 v16, v16, s98, v196
	v_fma_f32 v17, v17, s98, v196
	v_exp_f32_e32 v2, v2
	v_exp_f32_e32 v3, v3
	v_exp_f32_e32 v4, v4
	v_exp_f32_e32 v5, v5
	v_exp_f32_e32 v6, v6
	v_exp_f32_e32 v7, v7
	v_exp_f32_e32 v8, v8
	v_exp_f32_e32 v9, v9
	v_exp_f32_e32 v10, v10
	v_exp_f32_e32 v11, v11
	v_exp_f32_e32 v12, v12
	v_exp_f32_e32 v13, v13
	v_exp_f32_e32 v14, v14
	v_exp_f32_e32 v15, v15
	v_exp_f32_e32 v16, v16
	v_exp_f32_e32 v17, v17
	v_cmp_lt_f32_e32 vcc, v188, v194
	v_mov_b32_e32 v188, v194
	v_cvt_pk_bf16_f32 v98, v2, v3
	v_cvt_pk_bf16_f32 v99, v4, v5
	v_cvt_pk_bf16_f32 v100, v6, v7
	v_cvt_pk_bf16_f32 v101, v8, v9
	v_cvt_pk_bf16_f32 v102, v10, v11
	v_cvt_pk_bf16_f32 v103, v12, v13
	v_cvt_pk_bf16_f32 v104, v14, v15
	v_cvt_pk_bf16_f32 v105, v16, v17
	v_add_f32_e32 v206, v2, v3
	v_add_f32_e32 v207, v4, v5
	v_add_f32_e32 v208, v6, v7
	v_add_f32_e32 v209, v8, v9
	v_add_f32_e32 v206, v206, v10
	v_add_f32_e32 v207, v207, v11
	v_add_f32_e32 v208, v208, v12
	v_add_f32_e32 v209, v209, v13
	v_add_f32_e32 v206, v206, v14
	v_add_f32_e32 v207, v207, v15
	v_add_f32_e32 v208, v208, v16
	v_add_f32_e32 v209, v209, v17
	v_add_f32_e32 v206, v206, v207
	v_add_f32_e32 v208, v208, v209
	v_add_f32_e32 v206, v206, v208
	v_fmac_f32_e32 v206, v182, v190
	v_mov_b32_e32 v182, v206
	s_cbranch_vccz .Ldf_nr0b
	v_pk_mul_f32 v[82:83], v[82:83], v[190:191] op_sel_hi:[1,0]
	v_pk_mul_f32 v[84:85], v[84:85], v[190:191] op_sel_hi:[1,0]
	v_pk_mul_f32 v[86:87], v[86:87], v[190:191] op_sel_hi:[1,0]
	v_pk_mul_f32 v[88:89], v[88:89], v[190:191] op_sel_hi:[1,0]
	v_pk_mul_f32 v[90:91], v[90:91], v[190:191] op_sel_hi:[1,0]
	v_pk_mul_f32 v[92:93], v[92:93], v[190:191] op_sel_hi:[1,0]
	v_pk_mul_f32 v[94:95], v[94:95], v[190:191] op_sel_hi:[1,0]
	v_pk_mul_f32 v[96:97], v[96:97], v[190:191] op_sel_hi:[1,0]
	v_pk_mul_f32 v[66:67], v[66:67], v[190:191] op_sel_hi:[1,0]
	v_pk_mul_f32 v[68:69], v[68:69], v[190:191] op_sel_hi:[1,0]
	v_pk_mul_f32 v[70:71], v[70:71], v[190:191] op_sel_hi:[1,0]
	v_pk_mul_f32 v[72:73], v[72:73], v[190:191] op_sel_hi:[1,0]
	v_pk_mul_f32 v[74:75], v[74:75], v[190:191] op_sel_hi:[1,0]
	v_pk_mul_f32 v[76:77], v[76:77], v[190:191] op_sel_hi:[1,0]
	v_pk_mul_f32 v[78:79], v[78:79], v[190:191] op_sel_hi:[1,0]
	v_pk_mul_f32 v[80:81], v[80:81], v[190:191] op_sel_hi:[1,0]
	s_nop 1

.Ldf_sk1b:
	s_and_b64 vcc, exec, s[4:5]
	s_cbranch_vccnz .Ldf_exit
	s_add_i32 s15, s15, -1
	v_lshl_add_u64 v[180:181], v[180:181], 0, s[84:85]
	s_cmp_le_i32 s15, s73
	s_cselect_b64 s[4:5], -1, 0
	s_add_i32 s100, s15, -1
	s_cmp_le_i32 s15, s73
	s_cselect_b32 s76, s15, s100
	s_lshl_b64 s[16:17], s[76:77], 12
	s_waitcnt vmcnt(0)
	global_load_dwordx4 v[166:169], v[180:181], off offset:-2048
	global_load_dwordx4 v[162:165], v[180:181], off offset:-1024
	global_load_dwordx4 v[158:161], v[180:181], off
	global_load_dwordx4 v[154:157], v[180:181], off offset:1024
	v_lshl_add_u64 v[220:221], v[178:179], 0, s[16:17]
	global_load_dwordx4 v[146:149], v[220:221], off
	global_load_dwordx4 v[150:153], v[220:221], off offset:1024
	s_branch .Ldf_itera

.Lfx_itera:
	s_waitcnt lgkmcnt(0)
	v_mfma_f32_32x32x16_bf16 v[2:17], v[206:209], v[130:133], v[114:129]
	v_mfma_f32_32x32x16_bf16 v[18:33], v[206:209], v[146:149], v[114:129]
	v_mfma_f32_32x32x16_bf16 v[2:17], v[202:205], v[134:137], v[2:17]
	v_mfma_f32_32x32x16_bf16 v[18:33], v[202:205], v[150:153], v[18:33]
	v_mfma_f32_32x32x16_bf16 v[2:17], v[198:201], v[138:141], v[2:17]
	v_mfma_f32_32x32x16_bf16 v[18:33], v[198:201], v[154:157], v[18:33]
	v_mfma_f32_32x32x16_bf16 v[2:17], v[194:197], v[142:145], v[2:17]
	v_mfma_f32_32x32x16_bf16 v[18:33], v[194:197], v[158:161], v[18:33]
	s_nop 10
	v_max3_f32 v230, v2, v3, v4
	v_max3_f32 v231, v5, v6, v7
	v_max3_f32 v232, v8, v9, v10
	v_max3_f32 v233, v11, v12, v13
	v_max3_f32 v230, v230, v14, v15
	v_max3_f32 v231, v231, v16, v17
	v_max3_f32 v230, v230, v231, v232
	v_max_f32_e32 v230, v230, v233
	v_mul_f32_e32 v230, s98, v230
	v_mov_b32_e32 v231, v230
	s_nop 1
	v_permlane32_swap_b32_e32 v230, v231
	v_max3_f32 v220, v224, v230, v231
	v_sub_f32_e32 v232, v224, v220
	v_exp_f32_e32 v226, v232
	v_max_f32_e32 v233, v230, v231
	v_sub_f32_e32 v233, v233, v224
	v_cmp_lt_f32_e32 vcc, 0xc3180000, v233
	s_cbranch_vccz .Lfx_sk0a
	v_fma_f32 v2, v2, s98, -v220
	v_fma_f32 v3, v3, s98, -v220
	v_fma_f32 v4, v4, s98, -v220
	v_fma_f32 v5, v5, s98, -v220
	v_fma_f32 v6, v6, s98, -v220
	v_fma_f32 v7, v7, s98, -v220
	v_fma_f32 v8, v8, s98, -v220
	v_fma_f32 v9, v9, s98, -v220
	v_fma_f32 v10, v10, s98, -v220
	v_fma_f32 v11, v11, s98, -v220
	v_fma_f32 v12, v12, s98, -v220
	v_fma_f32 v13, v13, s98, -v220
	v_fma_f32 v14, v14, s98, -v220
	v_fma_f32 v15, v15, s98, -v220
	v_fma_f32 v16, v16, s98, -v220
	v_fma_f32 v17, v17, s98, -v220
	v_exp_f32_e32 v2, v2
	v_exp_f32_e32 v3, v3
	v_exp_f32_e32 v4, v4
	v_exp_f32_e32 v5, v5
	v_exp_f32_e32 v6, v6
	v_exp_f32_e32 v7, v7
	v_exp_f32_e32 v8, v8
	v_exp_f32_e32 v9, v9
	v_exp_f32_e32 v10, v10
	v_exp_f32_e32 v11, v11
	v_exp_f32_e32 v12, v12
	v_exp_f32_e32 v13, v13
	v_exp_f32_e32 v14, v14
	v_exp_f32_e32 v15, v15
	v_exp_f32_e32 v16, v16
	v_exp_f32_e32 v17, v17
	v_cmp_lt_f32_e32 vcc, v224, v220
	v_mov_b32_e32 v224, v220
	v_cvt_pk_bf16_f32 v98, v2, v3
	v_cvt_pk_bf16_f32 v99, v4, v5
	v_cvt_pk_bf16_f32 v100, v6, v7
	v_cvt_pk_bf16_f32 v101, v8, v9
	v_cvt_pk_bf16_f32 v102, v10, v11
	v_cvt_pk_bf16_f32 v103, v12, v13
	v_cvt_pk_bf16_f32 v104, v14, v15
	v_cvt_pk_bf16_f32 v105, v16, v17
	v_add_f32_e32 v230, v2, v3
	v_add_f32_e32 v231, v4, v5
	v_add_f32_e32 v232, v6, v7
	v_add_f32_e32 v233, v8, v9
	v_add_f32_e32 v230, v230, v10
	v_add_f32_e32 v231, v231, v11
	v_add_f32_e32 v232, v232, v12
	v_add_f32_e32 v233, v233, v13
	v_add_f32_e32 v230, v230, v14
	v_add_f32_e32 v231, v231, v15
	v_add_f32_e32 v232, v232, v16
	v_add_f32_e32 v233, v233, v17
	v_add_f32_e32 v230, v230, v231
	v_add_f32_e32 v232, v232, v233
	v_add_f32_e32 v230, v230, v232
	v_fmac_f32_e32 v230, v218, v226
	v_mov_b32_e32 v218, v230
	s_cbranch_vccz .Lfx_nr0a
	v_pk_mul_f32 v[82:83], v[82:83], v[226:227] op_sel_hi:[1,0]
	v_pk_mul_f32 v[84:85], v[84:85], v[226:227] op_sel_hi:[1,0]
	v_pk_mul_f32 v[86:87], v[86:87], v[226:227] op_sel_hi:[1,0]
	v_pk_mul_f32 v[88:89], v[88:89], v[226:227] op_sel_hi:[1,0]
	v_pk_mul_f32 v[90:91], v[90:91], v[226:227] op_sel_hi:[1,0]
	v_pk_mul_f32 v[92:93], v[92:93], v[226:227] op_sel_hi:[1,0]
	v_pk_mul_f32 v[94:95], v[94:95], v[226:227] op_sel_hi:[1,0]
	v_pk_mul_f32 v[96:97], v[96:97], v[226:227] op_sel_hi:[1,0]
	v_pk_mul_f32 v[66:67], v[66:67], v[226:227] op_sel_hi:[1,0]
	v_pk_mul_f32 v[68:69], v[68:69], v[226:227] op_sel_hi:[1,0]
	v_pk_mul_f32 v[70:71], v[70:71], v[226:227] op_sel_hi:[1,0]
	v_pk_mul_f32 v[72:73], v[72:73], v[226:227] op_sel_hi:[1,0]
	v_pk_mul_f32 v[74:75], v[74:75], v[226:227] op_sel_hi:[1,0]
	v_pk_mul_f32 v[76:77], v[76:77], v[226:227] op_sel_hi:[1,0]
	v_pk_mul_f32 v[78:79], v[78:79], v[226:227] op_sel_hi:[1,0]
	v_pk_mul_f32 v[80:81], v[80:81], v[226:227] op_sel_hi:[1,0]
	s_nop 1

.Lfx_sk0a:
	v_max3_f32 v230, v18, v19, v20
	v_max3_f32 v231, v21, v22, v23
	v_max3_f32 v232, v24, v25, v26
	v_max3_f32 v233, v27, v28, v29
	v_max3_f32 v230, v230, v30, v31
	v_max3_f32 v231, v231, v32, v33
	v_max3_f32 v230, v230, v231, v232
	v_max_f32_e32 v230, v230, v233
	v_mul_f32_e32 v230, s98, v230
	v_mov_b32_e32 v231, v230
	s_nop 1
	v_permlane32_swap_b32_e32 v230, v231
	v_max3_f32 v221, v225, v230, v231
	v_sub_f32_e32 v232, v225, v221
	v_exp_f32_e32 v228, v232
	v_max_f32_e32 v233, v230, v231
	v_sub_f32_e32 v233, v233, v225
	v_cmp_lt_f32_e32 vcc, 0xc3180000, v233
	s_cbranch_vccz .Lfx_sk1a
	v_fma_f32 v18, v18, s98, -v221
	v_fma_f32 v19, v19, s98, -v221
	v_fma_f32 v20, v20, s98, -v221
	v_fma_f32 v21, v21, s98, -v221
	v_fma_f32 v22, v22, s98, -v221
	v_fma_f32 v23, v23, s98, -v221
	v_fma_f32 v24, v24, s98, -v221
	v_fma_f32 v25, v25, s98, -v221
	v_fma_f32 v26, v26, s98, -v221
	v_fma_f32 v27, v27, s98, -v221
	v_fma_f32 v28, v28, s98, -v221
	v_fma_f32 v29, v29, s98, -v221
	v_fma_f32 v30, v30, s98, -v221
	v_fma_f32 v31, v31, s98, -v221
	v_fma_f32 v32, v32, s98, -v221
	v_fma_f32 v33, v33, s98, -v221
	v_exp_f32_e32 v18, v18
	v_exp_f32_e32 v19, v19
	v_exp_f32_e32 v20, v20
	v_exp_f32_e32 v21, v21
	v_exp_f32_e32 v22, v22
	v_exp_f32_e32 v23, v23
	v_exp_f32_e32 v24, v24
	v_exp_f32_e32 v25, v25
	v_exp_f32_e32 v26, v26
	v_exp_f32_e32 v27, v27
	v_exp_f32_e32 v28, v28
	v_exp_f32_e32 v29, v29
	v_exp_f32_e32 v30, v30
	v_exp_f32_e32 v31, v31
	v_exp_f32_e32 v32, v32
	v_exp_f32_e32 v33, v33
	v_cmp_lt_f32_e32 vcc, v225, v221
	v_mov_b32_e32 v225, v221
	v_cvt_pk_bf16_f32 v106, v18, v19
	v_cvt_pk_bf16_f32 v107, v20, v21
	v_cvt_pk_bf16_f32 v108, v22, v23
	v_cvt_pk_bf16_f32 v109, v24, v25
	v_cvt_pk_bf16_f32 v110, v26, v27
	v_cvt_pk_bf16_f32 v111, v28, v29
	v_cvt_pk_bf16_f32 v112, v30, v31
	v_cvt_pk_bf16_f32 v113, v32, v33
	v_add_f32_e32 v230, v18, v19
	v_add_f32_e32 v231, v20, v21
	v_add_f32_e32 v232, v22, v23
	v_add_f32_e32 v233, v24, v25
	v_add_f32_e32 v230, v230, v26
	v_add_f32_e32 v231, v231, v27
	v_add_f32_e32 v232, v232, v28
	v_add_f32_e32 v233, v233, v29
	v_add_f32_e32 v230, v230, v30
	v_add_f32_e32 v231, v231, v31
	v_add_f32_e32 v232, v232, v32
	v_add_f32_e32 v233, v233, v33
	v_add_f32_e32 v230, v230, v231
	v_add_f32_e32 v232, v232, v233
	v_add_f32_e32 v230, v230, v232
	v_fmac_f32_e32 v230, v219, v228
	v_mov_b32_e32 v219, v230
	s_cbranch_vccz .Lfx_nr1a
	v_pk_mul_f32 v[50:51], v[50:51], v[228:229] op_sel_hi:[1,0]
	v_pk_mul_f32 v[52:53], v[52:53], v[228:229] op_sel_hi:[1,0]
	v_pk_mul_f32 v[54:55], v[54:55], v[228:229] op_sel_hi:[1,0]
	v_pk_mul_f32 v[56:57], v[56:57], v[228:229] op_sel_hi:[1,0]
	v_pk_mul_f32 v[58:59], v[58:59], v[228:229] op_sel_hi:[1,0]
	v_pk_mul_f32 v[60:61], v[60:61], v[228:229] op_sel_hi:[1,0]
	v_pk_mul_f32 v[62:63], v[62:63], v[228:229] op_sel_hi:[1,0]
	v_pk_mul_f32 v[64:65], v[64:65], v[228:229] op_sel_hi:[1,0]
	v_pk_mul_f32 v[34:35], v[34:35], v[228:229] op_sel_hi:[1,0]
	v_pk_mul_f32 v[36:37], v[36:37], v[228:229] op_sel_hi:[1,0]
	v_pk_mul_f32 v[38:39], v[38:39], v[228:229] op_sel_hi:[1,0]
	v_pk_mul_f32 v[40:41], v[40:41], v[228:229] op_sel_hi:[1,0]
	v_pk_mul_f32 v[42:43], v[42:43], v[228:229] op_sel_hi:[1,0]
	v_pk_mul_f32 v[44:45], v[44:45], v[228:229] op_sel_hi:[1,0]
	v_pk_mul_f32 v[46:47], v[46:47], v[228:229] op_sel_hi:[1,0]
	v_pk_mul_f32 v[48:49], v[48:49], v[228:229] op_sel_hi:[1,0]
	s_nop 1
.Lfx_nr1a:
	s_waitcnt vmcnt(4)
	v_mfma_f32_32x32x16_bf16 v[50:65], v[190:193], v[106:109], v[50:65]
	v_mfma_f32_32x32x16_bf16 v[34:49], v[182:185], v[106:109], v[34:49]
	v_mfma_f32_32x32x16_bf16 v[50:65], v[186:189], v[110:113], v[50:65]
	v_mfma_f32_32x32x16_bf16 v[34:49], v[178:181], v[110:113], v[34:49]
.Lfx_sk1a:
	s_and_b64 vcc, exec, s[4:5]
	s_cbranch_vccnz .Lfx_exit
	s_add_i32 s14, s14, -1
	v_add_u32_e32 v0, 0xffffff7c, v0
	v_lshl_add_u64 v[216:217], v[216:217], 0, s[84:85]
	s_cmp_le_i32 s14, s73
	s_cselect_b64 s[4:5], -1, 0
	s_add_i32 s100, s14, -1
	s_cmp_le_i32 s14, s73
	s_cselect_b32 s76, s14, s100
	s_lshl_b64 s[16:17], s[76:77], 12
	ds_read2_b32 v[114:115], v0 offset1:1
	ds_read2_b32 v[116:117], v0 offset0:2 offset1:3
	ds_read2_b32 v[118:119], v0 offset0:8 offset1:9
	ds_read2_b32 v[120:121], v0 offset0:10 offset1:11
	ds_read2_b32 v[122:123], v0 offset0:16 offset1:17
	ds_read2_b32 v[124:125], v0 offset0:18 offset1:19
	ds_read2_b32 v[126:127], v0 offset0:24 offset1:25
	ds_read2_b32 v[128:129], v0 offset0:26 offset1:27
	s_waitcnt vmcnt(0)
	global_load_dwordx4 v[190:193], v[216:217], off offset:-2048
	global_load_dwordx4 v[186:189], v[216:217], off offset:-1024
	global_load_dwordx4 v[182:185], v[216:217], off
	global_load_dwordx4 v[178:181], v[216:217], off offset:1024
	v_lshl_add_u64 v[234:235], v[214:215], 0, s[16:17]
	global_load_dwordx4 v[206:209], v[234:235], off
	global_load_dwordx4 v[202:205], v[234:235], off offset:1024
	global_load_dwordx4 v[198:201], v[234:235], off offset:2048
	global_load_dwordx4 v[194:197], v[234:235], off offset:3072
	s_branch .Lfx_iterb
.Lfx_iterb:
	s_waitcnt lgkmcnt(0)
	v_mfma_f32_32x32x16_bf16 v[2:17], v[174:177], v[130:133], v[114:129]
	v_mfma_f32_32x32x16_bf16 v[18:33], v[174:177], v[146:149], v[114:129]
	v_mfma_f32_32x32x16_bf16 v[2:17], v[170:173], v[134:137], v[2:17]
	v_mfma_f32_32x32x16_bf16 v[18:33], v[170:173], v[150:153], v[18:33]
	v_mfma_f32_32x32x16_bf16 v[2:17], v[166:169], v[138:141], v[2:17]
	v_mfma_f32_32x32x16_bf16 v[18:33], v[166:169], v[154:157], v[18:33]
	v_mfma_f32_32x32x16_bf16 v[2:17], v[162:165], v[142:145], v[2:17]
	v_mfma_f32_32x32x16_bf16 v[18:33], v[162:165], v[158:161], v[18:33]
	s_nop 10
	v_max3_f32 v230, v2, v3, v4
	v_max3_f32 v231, v5, v6, v7
	v_max3_f32 v232, v8, v9, v10
	v_max3_f32 v233, v11, v12, v13
	v_max3_f32 v230, v230, v14, v15
	v_max3_f32 v231, v231, v16, v17
	v_max3_f32 v230, v230, v231, v232
	v_max_f32_e32 v230, v230, v233
	v_mul_f32_e32 v230, s98, v230
	v_mov_b32_e32 v231, v230
	s_nop 1
	v_permlane32_swap_b32_e32 v230, v231
	v_max3_f32 v220, v224, v230, v231
	v_sub_f32_e32 v232, v224, v220
	v_exp_f32_e32 v226, v232
	v_max_f32_e32 v233, v230, v231
	v_sub_f32_e32 v233, v233, v224
	v_cmp_lt_f32_e32 vcc, 0xc3180000, v233
	s_cbranch_vccz .Lfx_sk0b
	v_fma_f32 v2, v2, s98, -v220
	v_fma_f32 v3, v3, s98, -v220
	v_fma_f32 v4, v4, s98, -v220
	v_fma_f32 v5, v5, s98, -v220
	v_fma_f32 v6, v6, s98, -v220
	v_fma_f32 v7, v7, s98, -v220
	v_fma_f32 v8, v8, s98, -v220
	v_fma_f32 v9, v9, s98, -v220
	v_fma_f32 v10, v10, s98, -v220
	v_fma_f32 v11, v11, s98, -v220
	v_fma_f32 v12, v12, s98, -v220
	v_fma_f32 v13, v13, s98, -v220
	v_fma_f32 v14, v14, s98, -v220
	v_fma_f32 v15, v15, s98, -v220
	v_fma_f32 v16, v16, s98, -v220
	v_fma_f32 v17, v17, s98, -v220
	v_exp_f32_e32 v2, v2
	v_exp_f32_e32 v3, v3
	v_exp_f32_e32 v4, v4
	v_exp_f32_e32 v5, v5
	v_exp_f32_e32 v6, v6
	v_exp_f32_e32 v7, v7
	v_exp_f32_e32 v8, v8
	v_exp_f32_e32 v9, v9
	v_exp_f32_e32 v10, v10
	v_exp_f32_e32 v11, v11
	v_exp_f32_e32 v12, v12
	v_exp_f32_e32 v13, v13
	v_exp_f32_e32 v14, v14
	v_exp_f32_e32 v15, v15
	v_exp_f32_e32 v16, v16
	v_exp_f32_e32 v17, v17
	v_cmp_lt_f32_e32 vcc, v224, v220
	v_mov_b32_e32 v224, v220
	v_cvt_pk_bf16_f32 v98, v2, v3
	v_cvt_pk_bf16_f32 v99, v4, v5
	v_cvt_pk_bf16_f32 v100, v6, v7
	v_cvt_pk_bf16_f32 v101, v8, v9
	v_cvt_pk_bf16_f32 v102, v10, v11
	v_cvt_pk_bf16_f32 v103, v12, v13
	v_cvt_pk_bf16_f32 v104, v14, v15
	v_cvt_pk_bf16_f32 v105, v16, v17
	v_add_f32_e32 v230, v2, v3
	v_add_f32_e32 v231, v4, v5
	v_add_f32_e32 v232, v6, v7
	v_add_f32_e32 v233, v8, v9
	v_add_f32_e32 v230, v230, v10
	v_add_f32_e32 v231, v231, v11
	v_add_f32_e32 v232, v232, v12
	v_add_f32_e32 v233, v233, v13
	v_add_f32_e32 v230, v230, v14
	v_add_f32_e32 v231, v231, v15
	v_add_f32_e32 v232, v232, v16
	v_add_f32_e32 v233, v233, v17
	v_add_f32_e32 v230, v230, v231
	v_add_f32_e32 v232, v232, v233
	v_add_f32_e32 v230, v230, v232
	v_fmac_f32_e32 v230, v218, v226
	v_mov_b32_e32 v218, v230
	s_cbranch_vccz .Lfx_nr0b
	v_pk_mul_f32 v[82:83], v[82:83], v[226:227] op_sel_hi:[1,0]
	v_pk_mul_f32 v[84:85], v[84:85], v[226:227] op_sel_hi:[1,0]
	v_pk_mul_f32 v[86:87], v[86:87], v[226:227] op_sel_hi:[1,0]
	v_pk_mul_f32 v[88:89], v[88:89], v[226:227] op_sel_hi:[1,0]
	v_pk_mul_f32 v[90:91], v[90:91], v[226:227] op_sel_hi:[1,0]
	v_pk_mul_f32 v[92:93], v[92:93], v[226:227] op_sel_hi:[1,0]
	v_pk_mul_f32 v[94:95], v[94:95], v[226:227] op_sel_hi:[1,0]
	v_pk_mul_f32 v[96:97], v[96:97], v[226:227] op_sel_hi:[1,0]
	v_pk_mul_f32 v[66:67], v[66:67], v[226:227] op_sel_hi:[1,0]
	v_pk_mul_f32 v[68:69], v[68:69], v[226:227] op_sel_hi:[1,0]
	v_pk_mul_f32 v[70:71], v[70:71], v[226:227] op_sel_hi:[1,0]
	v_pk_mul_f32 v[72:73], v[72:73], v[226:227] op_sel_hi:[1,0]
	v_pk_mul_f32 v[74:75], v[74:75], v[226:227] op_sel_hi:[1,0]
	v_pk_mul_f32 v[76:77], v[76:77], v[226:227] op_sel_hi:[1,0]
	v_pk_mul_f32 v[78:79], v[78:79], v[226:227] op_sel_hi:[1,0]
	v_pk_mul_f32 v[80:81], v[80:81], v[226:227] op_sel_hi:[1,0]
	s_nop 1

.Lfx_sk1b:
	s_and_b64 vcc, exec, s[4:5]
	s_cbranch_vccnz .Lfx_exit
	s_add_i32 s14, s14, -1
	v_add_u32_e32 v0, 0xffffff7c, v0
	v_lshl_add_u64 v[216:217], v[216:217], 0, s[84:85]
	s_cmp_le_i32 s14, s73
	s_cselect_b64 s[4:5], -1, 0
	s_add_i32 s100, s14, -1
	s_cmp_le_i32 s14, s73
	s_cselect_b32 s76, s14, s100
	s_lshl_b64 s[16:17], s[76:77], 12
	ds_read2_b32 v[114:115], v0 offset1:1
	ds_read2_b32 v[116:117], v0 offset0:2 offset1:3
	ds_read2_b32 v[118:119], v0 offset0:8 offset1:9
	ds_read2_b32 v[120:121], v0 offset0:10 offset1:11
	ds_read2_b32 v[122:123], v0 offset0:16 offset1:17
	ds_read2_b32 v[124:125], v0 offset0:18 offset1:19
	ds_read2_b32 v[126:127], v0 offset0:24 offset1:25
	ds_read2_b32 v[128:129], v0 offset0:26 offset1:27
	s_waitcnt vmcnt(0)
	global_load_dwordx4 v[190:193], v[216:217], off offset:-2048
	global_load_dwordx4 v[186:189], v[216:217], off offset:-1024
	global_load_dwordx4 v[182:185], v[216:217], off
	global_load_dwordx4 v[178:181], v[216:217], off offset:1024
	v_lshl_add_u64 v[234:235], v[214:215], 0, s[16:17]
	global_load_dwordx4 v[174:177], v[234:235], off
	global_load_dwordx4 v[170:173], v[234:235], off offset:1024
	global_load_dwordx4 v[166:169], v[234:235], off offset:2048
	global_load_dwordx4 v[162:165], v[234:235], off offset:3072
	s_branch .Lfx_itera
